# mLSTM gate scans on wave 0: twelve LDS-permute round trips per scan pair replaced by DPP row-shift/broadcast prefix scans (f32 sum order changes slightly, max exact); m-state load issued early; on top
# speedup vs baseline: 1.0040x; 1.0040x over previous
.LBB0_534:
	s_or_b64 exec, exec, s[14:15]
	s_waitcnt vmcnt(1)
	ds_write_b128 v146, v[72:75] offset:34816
	s_waitcnt vmcnt(0)
	ds_write_b128 v146, v[68:71] offset:34832
	s_mov_b64 s[14:15], exec
	v_readlane_b32 s16, v254, 47
	v_readlane_b32 s17, v254, 48
	s_and_b64 s[16:17], s[14:15], s[16:17]
	s_mov_b64 exec, s[16:17]
	ds_write_b128 v166, v[44:47] offset:54272
	s_or_b64 exec, exec, s[14:15]
	s_mov_b64 s[14:15], exec
	v_readlane_b32 s16, v254, 49
	v_readlane_b32 s17, v254, 50
	s_and_b64 s[16:17], s[14:15], s[16:17]
	s_mov_b64 exec, s[16:17]
	ds_write_b128 v167, v[40:43] offset:54272
	s_or_b64 exec, exec, s[14:15]
	s_mov_b64 s[14:15], exec
	v_readlane_b32 s16, v254, 51
	v_readlane_b32 s17, v254, 52
	s_and_b64 s[16:17], s[14:15], s[16:17]
	s_mov_b64 exec, s[16:17]
	ds_write_b128 v168, v[56:59] offset:54272
	s_or_b64 exec, exec, s[14:15]
	s_mov_b64 s[14:15], exec
	v_readlane_b32 s16, v254, 53
	v_readlane_b32 s17, v254, 54
	s_and_b64 s[16:17], s[14:15], s[16:17]
	s_mov_b64 exec, s[16:17]
	ds_write_b128 v169, v[48:51] offset:54272
	s_or_b64 exec, exec, s[14:15]
	s_and_saveexec_b64 s[14:15], s[58:59]
	ds_write_b128 v170, v[64:67] offset:54272
	s_or_b64 exec, exec, s[14:15]
	ds_read_b128 v[40:43], v147
	ds_read_b128 v[44:47], v147 offset:16
	ds_read_b128 v[48:51], v148
	ds_read_b128 v[56:59], v148 offset:16
	v_lshlrev_b32_e32 v64, 16, v52
	v_and_b32_e32 v65, 0xffff0000, v52
	v_lshlrev_b32_e32 v52, 16, v53
	v_and_b32_e32 v53, 0xffff0000, v53
	s_waitcnt lgkmcnt(1)
	v_pk_fma_f32 v[48:49], v[48:49], v[64:65], v[40:41]
	v_pk_fma_f32 v[50:51], v[50:51], v[52:53], v[42:43]
	v_lshlrev_b32_e32 v40, 16, v54
	v_and_b32_e32 v41, 0xffff0000, v54
	v_lshlrev_b32_e32 v42, 16, v55
	v_and_b32_e32 v43, 0xffff0000, v55
	s_waitcnt lgkmcnt(0)
	v_pk_fma_f32 v[52:53], v[56:57], v[40:41], v[44:45]
	v_pk_fma_f32 v[54:55], v[58:59], v[42:43], v[46:47]
	ds_read_b128 v[44:47], v148 offset:512
	v_lshlrev_b32_e32 v40, 16, v60
	v_and_b32_e32 v41, 0xffff0000, v60
	v_lshlrev_b32_e32 v42, 16, v61
	v_and_b32_e32 v43, 0xffff0000, v61
	s_waitcnt lgkmcnt(0)
	v_pk_fma_f32 v[56:57], v[46:47], v[42:43], v[50:51]
	v_pk_fma_f32 v[58:59], v[44:45], v[40:41], v[48:49]
	ds_read_b128 v[48:51], v148 offset:528
	v_lshlrev_b32_e32 v44, 16, v62
	v_and_b32_e32 v45, 0xffff0000, v62
	v_lshlrev_b32_e32 v46, 16, v63
	v_and_b32_e32 v47, 0xffff0000, v63
	s_waitcnt lgkmcnt(0)
	v_pk_fma_f32 v[60:61], v[50:51], v[46:47], v[54:55]
	v_pk_fma_f32 v[62:63], v[48:49], v[44:45], v[52:53]
	ds_read_b128 v[52:55], v148 offset:1024
	v_lshlrev_b32_e32 v48, 16, v36
	v_and_b32_e32 v49, 0xffff0000, v36
	v_lshlrev_b32_e32 v50, 16, v37
	v_and_b32_e32 v51, 0xffff0000, v37
	s_waitcnt lgkmcnt(0)
	v_pk_fma_f32 v[64:65], v[52:53], v[48:49], v[58:59]
	v_pk_fma_f32 v[66:67], v[54:55], v[50:51], v[56:57]
	ds_read_b128 v[52:55], v148 offset:1040
	v_lshlrev_b32_e32 v36, 16, v38
	v_and_b32_e32 v37, 0xffff0000, v38
	v_lshlrev_b32_e32 v38, 16, v39
	v_and_b32_e32 v39, 0xffff0000, v39
	s_waitcnt lgkmcnt(0)
	v_pk_fma_f32 v[68:69], v[54:55], v[38:39], v[60:61]
	ds_read_b128 v[58:61], v148 offset:1536
	v_lshlrev_b32_e32 v54, 16, v32
	v_and_b32_e32 v55, 0xffff0000, v32
	v_lshlrev_b32_e32 v56, 16, v33
	v_and_b32_e32 v57, 0xffff0000, v33
	s_waitcnt lgkmcnt(0)
	v_pk_fma_f32 v[66:67], v[60:61], v[56:57], v[66:67]
	v_pk_fma_f32 v[64:65], v[58:59], v[54:55], v[64:65]
	ds_read_b128 v[58:61], v148 offset:1552
	v_lshlrev_b32_e32 v32, 16, v35
	v_and_b32_e32 v33, 0xffff0000, v35
	v_pk_fma_f32 v[62:63], v[52:53], v[36:37], v[62:63]
	v_lshlrev_b32_e32 v52, 16, v34
	v_and_b32_e32 v53, 0xffff0000, v34
	s_waitcnt lgkmcnt(0)
	v_pk_fma_f32 v[34:35], v[60:61], v[32:33], v[68:69]
	v_mul_f32_e32 v60, 0xbfb8aa3b, v64
	v_mul_f32_e32 v61, 0xbfb8aa3b, v65
	v_exp_f32_e32 v60, v60
	v_exp_f32_e32 v61, v61
	v_pk_fma_f32 v[58:59], v[58:59], v[52:53], v[62:63]
	s_mov_b32 s14, 0x3db504f3
	v_add_f32_e32 v60, 1.0, v60
	v_add_f32_e32 v61, 1.0, v61
	v_rcp_f32_e32 v60, v60
	v_rcp_f32_e32 v61, v61
	v_mul_f32_e32 v62, 0xbfb8aa3b, v66
	v_mul_f32_e32 v63, 0xbfb8aa3b, v67
	v_exp_f32_e32 v62, v62
	v_pk_mul_f32 v[60:61], v[64:65], v[60:61]
	v_mul_f32_e32 v64, 0xbfb8aa3b, v58
	v_mul_f32_e32 v65, 0xbfb8aa3b, v59
	v_exp_f32_e32 v64, v64
	v_exp_f32_e32 v65, v65
	v_exp_f32_e32 v63, v63
	v_add_f32_e32 v62, 1.0, v62
	v_add_f32_e32 v64, 1.0, v64
	v_add_f32_e32 v65, 1.0, v65
	v_rcp_f32_e32 v64, v64
	v_rcp_f32_e32 v65, v65
	v_add_f32_e32 v63, 1.0, v63
	v_rcp_f32_e32 v62, v62
	v_rcp_f32_e32 v63, v63
	v_pk_mul_f32 v[58:59], v[58:59], v[64:65]
	v_pk_mul_f32 v[60:61], v[60:61], s[14:15] op_sel_hi:[1,0]
	v_pk_mul_f32 v[64:65], v[58:59], s[14:15] op_sel_hi:[1,0]
	v_mul_f32_e32 v58, 0xbfb8aa3b, v34
	v_mul_f32_e32 v59, 0xbfb8aa3b, v35
	v_exp_f32_e32 v58, v58
	v_exp_f32_e32 v59, v59
	v_pk_mul_f32 v[62:63], v[66:67], v[62:63]
	s_and_b64 vcc, exec, s[12:13]
	v_add_f32_e32 v58, 1.0, v58
	v_add_f32_e32 v59, 1.0, v59
	v_rcp_f32_e32 v58, v58
	v_rcp_f32_e32 v59, v59
	v_pk_mul_f32 v[62:63], v[62:63], s[14:15] op_sel_hi:[1,0]
	v_pk_mul_f32 v[34:35], v[34:35], v[58:59]
	s_nop 0
	v_pk_mul_f32 v[34:35], v[34:35], s[14:15] op_sel_hi:[1,0]
	v_cvt_pk_bf16_f32 v58, v60, v61
	v_cvt_pk_bf16_f32 v59, v62, v63
	v_cvt_pk_bf16_f32 v60, v64, v65
	v_cvt_pk_bf16_f32 v61, v34, v35
	ds_write_b128 v171, v[58:61]
	ds_read_b128 v[58:61], v147
	ds_read_b128 v[62:65], v147 offset:16
	ds_read_b128 v[66:69], v148
	ds_read_b128 v[70:73], v148 offset:16
	s_waitcnt lgkmcnt(1)
	v_pk_fma_f32 v[34:35], v[66:67], v[40:41], v[58:59]
	v_pk_fma_f32 v[58:59], v[68:69], v[42:43], v[60:61]
	ds_read_b128 v[40:43], v148 offset:512
	s_waitcnt lgkmcnt(1)
	v_pk_fma_f32 v[44:45], v[70:71], v[44:45], v[62:63]
	v_pk_fma_f32 v[46:47], v[72:73], v[46:47], v[64:65]
	s_waitcnt lgkmcnt(0)
	v_pk_fma_f32 v[50:51], v[42:43], v[50:51], v[58:59]
	v_pk_fma_f32 v[48:49], v[40:41], v[48:49], v[34:35]
	ds_read_b128 v[40:43], v148 offset:528
	s_waitcnt lgkmcnt(0)
	v_pk_fma_f32 v[40:41], v[40:41], v[36:37], v[44:45]
	ds_read_b128 v[34:37], v148 offset:1024
	v_pk_fma_f32 v[38:39], v[42:43], v[38:39], v[46:47]
	s_waitcnt lgkmcnt(0)
	v_pk_fma_f32 v[42:43], v[34:35], v[54:55], v[48:49]
	v_pk_fma_f32 v[44:45], v[36:37], v[56:57], v[50:51]
	ds_read_b128 v[34:37], v148 offset:1040
	s_waitcnt lgkmcnt(0)
	v_pk_fma_f32 v[40:41], v[34:35], v[52:53], v[40:41]
	v_pk_fma_f32 v[36:37], v[36:37], v[32:33], v[38:39]
	ds_read_b128 v[32:35], v148 offset:1536
	v_lshlrev_b32_e32 v38, 16, v28
	v_and_b32_e32 v39, 0xffff0000, v28
	v_lshlrev_b32_e32 v28, 16, v29
	v_and_b32_e32 v29, 0xffff0000, v29
	s_waitcnt lgkmcnt(0)
	v_pk_fma_f32 v[34:35], v[34:35], v[28:29], v[44:45]
	v_pk_fma_f32 v[32:33], v[32:33], v[38:39], v[42:43]
	v_lshlrev_b32_e32 v38, 16, v30
	v_and_b32_e32 v39, 0xffff0000, v30
	v_lshlrev_b32_e32 v42, 16, v31
	v_and_b32_e32 v43, 0xffff0000, v31
	ds_read_b128 v[28:31], v148 offset:1552
	v_lshlrev_b32_e32 v44, 16, v24
	v_and_b32_e32 v45, 0xffff0000, v24
	v_lshlrev_b32_e32 v24, 16, v25
	v_and_b32_e32 v25, 0xffff0000, v25
	s_waitcnt lgkmcnt(0)
	v_pk_fma_f32 v[30:31], v[30:31], v[42:43], v[36:37]
	v_mul_f32_e32 v36, 0xbfb8aa3b, v32
	v_mul_f32_e32 v37, 0xbfb8aa3b, v33
	v_exp_f32_e32 v36, v36
	v_exp_f32_e32 v37, v37
	v_pk_fma_f32 v[28:29], v[28:29], v[38:39], v[40:41]
	v_add_f32_e32 v36, 1.0, v36
	v_add_f32_e32 v37, 1.0, v37
	v_rcp_f32_e32 v36, v36
	v_rcp_f32_e32 v37, v37
	s_nop 0
	v_pk_mul_f32 v[32:33], v[32:33], v[36:37]
	v_mul_f32_e32 v36, 0xbfb8aa3b, v34
	v_mul_f32_e32 v37, 0xbfb8aa3b, v35
	v_exp_f32_e32 v36, v36
	v_exp_f32_e32 v37, v37
	v_pk_mul_f32 v[32:33], v[32:33], s[14:15] op_sel_hi:[1,0]
	v_add_f32_e32 v36, 1.0, v36
	v_add_f32_e32 v37, 1.0, v37
	v_rcp_f32_e32 v36, v36
	v_rcp_f32_e32 v37, v37
	s_nop 0
	v_pk_mul_f32 v[34:35], v[34:35], v[36:37]
	v_mul_f32_e32 v36, 0xbfb8aa3b, v28
	v_mul_f32_e32 v37, 0xbfb8aa3b, v29
	v_exp_f32_e32 v36, v36
	v_exp_f32_e32 v37, v37
	v_pk_mul_f32 v[34:35], v[34:35], s[14:15] op_sel_hi:[1,0]
	v_add_f32_e32 v36, 1.0, v36
	v_add_f32_e32 v37, 1.0, v37
	v_rcp_f32_e32 v36, v36
	v_rcp_f32_e32 v37, v37
	s_nop 0
	v_pk_mul_f32 v[28:29], v[28:29], v[36:37]
	s_nop 0
	v_pk_mul_f32 v[36:37], v[28:29], s[14:15] op_sel_hi:[1,0]
	v_mul_f32_e32 v28, 0xbfb8aa3b, v30
	v_mul_f32_e32 v29, 0xbfb8aa3b, v31
	v_exp_f32_e32 v28, v28
	v_exp_f32_e32 v29, v29
	v_add_f32_e32 v28, 1.0, v28
	v_add_f32_e32 v29, 1.0, v29
	v_rcp_f32_e32 v28, v28
	v_rcp_f32_e32 v29, v29
	s_nop 0
	v_pk_mul_f32 v[28:29], v[30:31], v[28:29]
	s_nop 0
	v_pk_mul_f32 v[38:39], v[28:29], s[14:15] op_sel_hi:[1,0]
	v_cvt_pk_bf16_f32 v28, v32, v33
	v_cvt_pk_bf16_f32 v29, v34, v35
	v_cvt_pk_bf16_f32 v30, v36, v37
	v_cvt_pk_bf16_f32 v31, v38, v39
	ds_write_b128 v171, v[28:31] offset:272
	ds_read_b128 v[28:31], v147 offset:512
	ds_read_b128 v[32:35], v147 offset:528
	ds_read_b128 v[36:39], v148 offset:2048
	ds_read_b128 v[40:43], v148 offset:2064
	s_waitcnt lgkmcnt(1)
	v_pk_fma_f32 v[30:31], v[38:39], v[24:25], v[30:31]
	v_lshlrev_b32_e32 v24, 16, v26
	v_and_b32_e32 v25, 0xffff0000, v26
	v_lshlrev_b32_e32 v26, 16, v27
	v_and_b32_e32 v27, 0xffff0000, v27
	v_pk_fma_f32 v[36:37], v[36:37], v[44:45], v[28:29]
	s_waitcnt lgkmcnt(0)
	v_pk_fma_f32 v[34:35], v[42:43], v[26:27], v[34:35]
	ds_read_b128 v[26:29], v148 offset:2560
	v_pk_fma_f32 v[32:33], v[40:41], v[24:25], v[32:33]
	v_lshlrev_b32_e32 v24, 16, v20
	v_and_b32_e32 v25, 0xffff0000, v20
	v_lshlrev_b32_e32 v20, 16, v21
	v_and_b32_e32 v21, 0xffff0000, v21
	s_waitcnt lgkmcnt(0)
	v_pk_fma_f32 v[38:39], v[28:29], v[20:21], v[30:31]
	ds_read_b128 v[28:31], v148 offset:2576
	v_pk_fma_f32 v[36:37], v[26:27], v[24:25], v[36:37]
	v_lshlrev_b32_e32 v26, 16, v22
	v_and_b32_e32 v27, 0xffff0000, v22
	v_lshlrev_b32_e32 v22, 16, v23
	v_and_b32_e32 v23, 0xffff0000, v23
	s_waitcnt lgkmcnt(0)
	v_pk_fma_f32 v[40:41], v[30:31], v[22:23], v[34:35]
	v_pk_fma_f32 v[42:43], v[28:29], v[26:27], v[32:33]
	ds_read_b128 v[32:35], v148 offset:3072
	v_lshlrev_b32_e32 v28, 16, v16
	v_and_b32_e32 v29, 0xffff0000, v16
	v_lshlrev_b32_e32 v30, 16, v17
	v_and_b32_e32 v31, 0xffff0000, v17
	s_waitcnt lgkmcnt(0)
	v_pk_fma_f32 v[44:45], v[32:33], v[28:29], v[36:37]
	v_pk_fma_f32 v[46:47], v[34:35], v[30:31], v[38:39]
	ds_read_b128 v[32:35], v148 offset:3088
	v_lshlrev_b32_e32 v16, 16, v18
	v_and_b32_e32 v17, 0xffff0000, v18
	v_lshlrev_b32_e32 v18, 16, v19
	v_and_b32_e32 v19, 0xffff0000, v19
	s_waitcnt lgkmcnt(0)
	v_pk_fma_f32 v[48:49], v[34:35], v[18:19], v[40:41]
	ds_read_b128 v[38:41], v148 offset:3584
	v_lshlrev_b32_e32 v34, 16, v12
	v_and_b32_e32 v35, 0xffff0000, v12
	v_lshlrev_b32_e32 v36, 16, v13
	v_and_b32_e32 v37, 0xffff0000, v13
	s_waitcnt lgkmcnt(0)
	v_pk_fma_f32 v[46:47], v[40:41], v[36:37], v[46:47]
	v_pk_fma_f32 v[44:45], v[38:39], v[34:35], v[44:45]
	ds_read_b128 v[38:41], v148 offset:3600
	v_lshlrev_b32_e32 v12, 16, v15
	v_and_b32_e32 v13, 0xffff0000, v15
	v_pk_fma_f32 v[42:43], v[32:33], v[16:17], v[42:43]
	v_lshlrev_b32_e32 v32, 16, v14
	v_and_b32_e32 v33, 0xffff0000, v14
	s_waitcnt lgkmcnt(0)
	v_pk_fma_f32 v[14:15], v[40:41], v[12:13], v[48:49]
	v_mul_f32_e32 v40, 0xbfb8aa3b, v44
	v_mul_f32_e32 v41, 0xbfb8aa3b, v45
	v_exp_f32_e32 v40, v40
	v_exp_f32_e32 v41, v41
	v_pk_fma_f32 v[38:39], v[38:39], v[32:33], v[42:43]
	v_mul_f32_e32 v42, 0xbfb8aa3b, v46
	v_add_f32_e32 v40, 1.0, v40
	v_add_f32_e32 v41, 1.0, v41
	v_rcp_f32_e32 v40, v40
	v_rcp_f32_e32 v41, v41
	v_mul_f32_e32 v43, 0xbfb8aa3b, v47
	v_exp_f32_e32 v42, v42
	v_exp_f32_e32 v43, v43
	v_pk_mul_f32 v[40:41], v[44:45], v[40:41]
	v_mul_f32_e32 v44, 0xbfb8aa3b, v38
	v_mul_f32_e32 v45, 0xbfb8aa3b, v39
	v_exp_f32_e32 v44, v44
	v_exp_f32_e32 v45, v45
	v_add_f32_e32 v42, 1.0, v42
	v_add_f32_e32 v43, 1.0, v43
	v_add_f32_e32 v44, 1.0, v44
	v_add_f32_e32 v45, 1.0, v45
	v_rcp_f32_e32 v44, v44
	v_rcp_f32_e32 v45, v45
	v_rcp_f32_e32 v42, v42
	v_rcp_f32_e32 v43, v43
	v_pk_mul_f32 v[44:45], v[38:39], v[44:45]
	v_mul_f32_e32 v38, 0xbfb8aa3b, v14
	v_mul_f32_e32 v39, 0xbfb8aa3b, v15
	v_exp_f32_e32 v38, v38
	v_exp_f32_e32 v39, v39
	v_pk_mul_f32 v[42:43], v[46:47], v[42:43]
	v_add_f32_e32 v38, 1.0, v38
	v_add_f32_e32 v39, 1.0, v39
	v_rcp_f32_e32 v38, v38
	v_rcp_f32_e32 v39, v39
	s_nop 0
	v_pk_mul_f32 v[14:15], v[14:15], v[38:39]
	v_cvt_pk_bf16_f32 v38, v40, v41
	v_cvt_pk_bf16_f32 v39, v42, v43
	v_cvt_pk_bf16_f32 v40, v44, v45
	v_cvt_pk_bf16_f32 v41, v14, v15
	ds_write_b128 v171, v[38:41] offset:17408
	ds_read_b128 v[38:41], v147 offset:512
	ds_read_b128 v[42:45], v147 offset:528
	ds_read_b128 v[46:49], v148 offset:2048
	ds_read_b128 v[50:53], v148 offset:2064
	s_waitcnt lgkmcnt(1)
	v_pk_fma_f32 v[14:15], v[46:47], v[24:25], v[38:39]
	v_pk_fma_f32 v[24:25], v[48:49], v[20:21], v[40:41]
	s_waitcnt lgkmcnt(0)
	v_pk_fma_f32 v[38:39], v[52:53], v[22:23], v[44:45]
	ds_read_b128 v[20:23], v148 offset:2560
	v_pk_fma_f32 v[26:27], v[50:51], v[26:27], v[42:43]
	s_waitcnt lgkmcnt(0)
	v_pk_fma_f32 v[24:25], v[22:23], v[30:31], v[24:25]
	v_pk_fma_f32 v[28:29], v[20:21], v[28:29], v[14:15]
	ds_read_b128 v[20:23], v148 offset:2576
	s_waitcnt lgkmcnt(0)
	v_pk_fma_f32 v[20:21], v[20:21], v[16:17], v[26:27]
	ds_read_b128 v[14:17], v148 offset:3072
	v_pk_fma_f32 v[18:19], v[22:23], v[18:19], v[38:39]
	s_waitcnt lgkmcnt(0)
	v_pk_fma_f32 v[22:23], v[14:15], v[34:35], v[28:29]
	v_pk_fma_f32 v[24:25], v[16:17], v[36:37], v[24:25]
	ds_read_b128 v[14:17], v148 offset:3088
	s_waitcnt lgkmcnt(0)
	v_pk_fma_f32 v[20:21], v[14:15], v[32:33], v[20:21]
	v_pk_fma_f32 v[16:17], v[16:17], v[12:13], v[18:19]
	ds_read_b128 v[12:15], v148 offset:3584
	v_lshlrev_b32_e32 v18, 16, v8
	v_and_b32_e32 v19, 0xffff0000, v8
	v_lshlrev_b32_e32 v8, 16, v9
	v_and_b32_e32 v9, 0xffff0000, v9
	s_waitcnt lgkmcnt(0)
	v_pk_fma_f32 v[14:15], v[14:15], v[8:9], v[24:25]
	v_pk_fma_f32 v[12:13], v[12:13], v[18:19], v[22:23]
	v_lshlrev_b32_e32 v18, 16, v10
	v_and_b32_e32 v19, 0xffff0000, v10
	v_lshlrev_b32_e32 v22, 16, v11
	v_and_b32_e32 v23, 0xffff0000, v11
	ds_read_b128 v[8:11], v148 offset:3600
	s_waitcnt lgkmcnt(0)
	v_pk_fma_f32 v[10:11], v[10:11], v[22:23], v[16:17]
	v_mul_f32_e32 v16, 0xbfb8aa3b, v12
	v_mul_f32_e32 v17, 0xbfb8aa3b, v13
	v_exp_f32_e32 v16, v16
	v_exp_f32_e32 v17, v17
	v_pk_fma_f32 v[8:9], v[8:9], v[18:19], v[20:21]
	v_add_f32_e32 v16, 1.0, v16
	v_add_f32_e32 v17, 1.0, v17
	v_rcp_f32_e32 v16, v16
	v_rcp_f32_e32 v17, v17
	s_nop 0
	v_pk_mul_f32 v[12:13], v[12:13], v[16:17]
	v_mul_f32_e32 v16, 0xbfb8aa3b, v14
	v_mul_f32_e32 v17, 0xbfb8aa3b, v15
	v_exp_f32_e32 v16, v16
	v_exp_f32_e32 v17, v17
	v_add_f32_e32 v16, 1.0, v16
	v_add_f32_e32 v17, 1.0, v17
	v_rcp_f32_e32 v16, v16
	v_rcp_f32_e32 v17, v17
	s_nop 0
	v_pk_mul_f32 v[14:15], v[14:15], v[16:17]
	v_mul_f32_e32 v16, 0xbfb8aa3b, v8
	v_mul_f32_e32 v17, 0xbfb8aa3b, v9
	v_exp_f32_e32 v16, v16
	v_exp_f32_e32 v17, v17
	v_add_f32_e32 v16, 1.0, v16
	v_add_f32_e32 v17, 1.0, v17
	v_rcp_f32_e32 v16, v16
	v_rcp_f32_e32 v17, v17
	s_nop 0
	v_pk_mul_f32 v[16:17], v[8:9], v[16:17]
	v_mul_f32_e32 v8, 0xbfb8aa3b, v10
	v_mul_f32_e32 v9, 0xbfb8aa3b, v11
	v_exp_f32_e32 v8, v8
	v_exp_f32_e32 v9, v9
	v_add_f32_e32 v8, 1.0, v8
	v_add_f32_e32 v9, 1.0, v9
	v_rcp_f32_e32 v8, v8
	v_rcp_f32_e32 v9, v9
	s_nop 0
	v_pk_mul_f32 v[18:19], v[10:11], v[8:9]
	v_cvt_pk_bf16_f32 v8, v12, v13
	v_cvt_pk_bf16_f32 v9, v14, v15
	v_cvt_pk_bf16_f32 v10, v16, v17
	v_cvt_pk_bf16_f32 v11, v18, v19
	ds_write_b128 v171, v[8:11] offset:17680
	s_cbranch_vccnz .LBB0_546
	v_mov_b32_e32 v10, v77
	s_ashr_i32 s9, s8, 31
	s_lshl_b64 s[12:13], s[8:9], 2
	v_readlane_b32 s9, v251, 53
	s_add_u32 s12, s9, s12
	v_readlane_b32 s9, v251, 54
	s_addc_u32 s13, s9, s13
	s_nop 0
	global_load_dword v14, v181, s[12:13]
	s_nop 1
	v_add_f32_dpp v10, v10, v10 row_shr:1 row_mask:0xf bank_mask:0xf
	s_nop 1
	v_add_f32_dpp v10, v10, v10 row_shr:2 row_mask:0xf bank_mask:0xf
	s_nop 1
	v_add_f32_dpp v10, v10, v10 row_shr:4 row_mask:0xf bank_mask:0xf
	s_nop 1
	v_add_f32_dpp v10, v10, v10 row_shr:8 row_mask:0xf bank_mask:0xf
	s_nop 1
	v_add_f32_dpp v10, v10, v10 row_bcast:15 row_mask:0xa bank_mask:0xf
	s_nop 1
	v_add_f32_dpp v10, v10, v10 row_bcast:31 row_mask:0xc bank_mask:0xf
	v_sub_f32_e32 v15, v76, v10
	ds_write2st64_b32 v149, v10, v15 offset1:1
	v_mov_b32_e32 v9, v15
	s_nop 1
	v_max_f32_dpp v9, v9, v9 row_shr:1 row_mask:0xf bank_mask:0xf
	s_nop 1
	v_max_f32_dpp v9, v9, v9 row_shr:2 row_mask:0xf bank_mask:0xf
	s_nop 1
	v_max_f32_dpp v9, v9, v9 row_shr:4 row_mask:0xf bank_mask:0xf
	s_nop 1
	v_max_f32_dpp v9, v9, v9 row_shr:8 row_mask:0xf bank_mask:0xf
	s_nop 1
	v_max_f32_dpp v9, v9, v9 row_bcast:15 row_mask:0xa bank_mask:0xf
	s_nop 1
	v_max_f32_dpp v9, v9, v9 row_bcast:31 row_mask:0xc bank_mask:0xf
	v_max_f32_e32 v8, v9, v9
	s_waitcnt vmcnt(0)
	v_max_f32_e32 v11, v14, v14
	v_max_f32_e32 v8, v8, v11
	v_add_f32_e32 v8, v10, v8
	v_add_f32_e32 v9, v14, v10
	v_sub_f32_e32 v9, v9, v8
	v_mul_f32_e32 v9, 0x3fb8aa3b, v9
	v_exp_f32_e32 v9, v9
	ds_write2st64_b32 v149, v8, v9 offset0:2 offset1:3
	v_mul_f32_e32 v8, 0xbfb8aa3b, v8
	v_exp_f32_e32 v8, v8
	ds_write_b32 v149, v8 offset:1280

.LBB0_566:
	s_or_b64 exec, exec, s[14:15]
	s_waitcnt vmcnt(1)
	ds_write_b128 v146, v[32:35] offset:34816
	s_waitcnt vmcnt(0)
	ds_write_b128 v146, v[28:31] offset:34832
	ds_read_b128 v[28:31], v161
	ds_read_b128 v[32:35], v161 offset:16
	ds_read_b128 v[40:43], v162
	s_waitcnt lgkmcnt(6)
	ds_read_b128 v[44:47], v162 offset:16
	v_lshlrev_b32_e32 v36, 16, v24
	v_and_b32_e32 v37, 0xffff0000, v24
	v_lshlrev_b32_e32 v24, 16, v25
	v_and_b32_e32 v25, 0xffff0000, v25
	s_waitcnt lgkmcnt(1)
	v_pk_fma_f32 v[30:31], v[42:43], v[24:25], v[30:31]
	v_lshlrev_b32_e32 v24, 16, v26
	v_and_b32_e32 v25, 0xffff0000, v26
	v_lshlrev_b32_e32 v26, 16, v27
	v_and_b32_e32 v27, 0xffff0000, v27
	v_pk_fma_f32 v[36:37], v[40:41], v[36:37], v[28:29]
	s_waitcnt lgkmcnt(0)
	v_pk_fma_f32 v[34:35], v[46:47], v[26:27], v[34:35]
	ds_read_b128 v[26:29], v162 offset:512
	v_pk_fma_f32 v[32:33], v[44:45], v[24:25], v[32:33]
	v_lshlrev_b32_e32 v24, 16, v20
	v_and_b32_e32 v25, 0xffff0000, v20
	v_lshlrev_b32_e32 v20, 16, v21
	v_and_b32_e32 v21, 0xffff0000, v21
	s_waitcnt lgkmcnt(0)
	v_pk_fma_f32 v[40:41], v[28:29], v[20:21], v[30:31]
	ds_read_b128 v[28:31], v162 offset:528
	v_pk_fma_f32 v[36:37], v[26:27], v[24:25], v[36:37]
	v_lshlrev_b32_e32 v26, 16, v22
	v_and_b32_e32 v27, 0xffff0000, v22
	v_lshlrev_b32_e32 v22, 16, v23
	v_and_b32_e32 v23, 0xffff0000, v23
	s_waitcnt lgkmcnt(0)
	v_pk_fma_f32 v[42:43], v[30:31], v[22:23], v[34:35]
	v_pk_fma_f32 v[44:45], v[28:29], v[26:27], v[32:33]
	ds_read_b128 v[32:35], v162 offset:1024
	v_lshlrev_b32_e32 v28, 16, v16
	v_and_b32_e32 v29, 0xffff0000, v16
	v_lshlrev_b32_e32 v30, 16, v17
	v_and_b32_e32 v31, 0xffff0000, v17
	s_waitcnt lgkmcnt(0)
	v_pk_fma_f32 v[46:47], v[32:33], v[28:29], v[36:37]
	v_pk_fma_f32 v[48:49], v[34:35], v[30:31], v[40:41]
	ds_read_b128 v[32:35], v162 offset:1040
	v_lshlrev_b32_e32 v16, 16, v18
	v_and_b32_e32 v17, 0xffff0000, v18
	v_lshlrev_b32_e32 v18, 16, v19
	v_and_b32_e32 v19, 0xffff0000, v19
	s_waitcnt lgkmcnt(0)
	v_pk_fma_f32 v[50:51], v[34:35], v[18:19], v[42:43]
	ds_read_b128 v[40:43], v162 offset:1536
	v_lshlrev_b32_e32 v34, 16, v12
	v_and_b32_e32 v35, 0xffff0000, v12
	v_lshlrev_b32_e32 v36, 16, v13
	v_and_b32_e32 v37, 0xffff0000, v13
	s_waitcnt lgkmcnt(0)
	v_pk_fma_f32 v[48:49], v[42:43], v[36:37], v[48:49]
	v_pk_fma_f32 v[46:47], v[40:41], v[34:35], v[46:47]
	ds_read_b128 v[40:43], v162 offset:1552
	v_lshlrev_b32_e32 v12, 16, v15
	v_and_b32_e32 v13, 0xffff0000, v15
	v_pk_fma_f32 v[44:45], v[32:33], v[16:17], v[44:45]
	v_lshlrev_b32_e32 v32, 16, v14
	v_and_b32_e32 v33, 0xffff0000, v14
	s_waitcnt lgkmcnt(0)
	v_pk_fma_f32 v[14:15], v[42:43], v[12:13], v[50:51]
	v_mul_f32_e32 v42, 0xbfb8aa3b, v46
	v_mul_f32_e32 v43, 0xbfb8aa3b, v47
	v_exp_f32_e32 v42, v42
	v_exp_f32_e32 v43, v43
	v_pk_fma_f32 v[40:41], v[40:41], v[32:33], v[44:45]
	v_mul_f32_e32 v44, 0xbfb8aa3b, v48
	v_add_f32_e32 v42, 1.0, v42
	v_add_f32_e32 v43, 1.0, v43
	v_rcp_f32_e32 v42, v42
	v_rcp_f32_e32 v43, v43
	v_mul_f32_e32 v45, 0xbfb8aa3b, v49
	v_exp_f32_e32 v44, v44
	v_exp_f32_e32 v45, v45
	v_pk_mul_f32 v[42:43], v[46:47], v[42:43]
	v_mul_f32_e32 v46, 0xbfb8aa3b, v40
	v_mul_f32_e32 v47, 0xbfb8aa3b, v41
	v_exp_f32_e32 v46, v46
	v_exp_f32_e32 v47, v47
	v_add_f32_e32 v44, 1.0, v44
	v_add_f32_e32 v45, 1.0, v45
	v_add_f32_e32 v46, 1.0, v46
	v_add_f32_e32 v47, 1.0, v47
	v_rcp_f32_e32 v46, v46
	v_rcp_f32_e32 v47, v47
	v_rcp_f32_e32 v44, v44
	v_rcp_f32_e32 v45, v45
	s_and_b64 vcc, exec, s[12:13]
	v_pk_mul_f32 v[46:47], v[40:41], v[46:47]
	v_mul_f32_e32 v40, 0xbfb8aa3b, v14
	v_mul_f32_e32 v41, 0xbfb8aa3b, v15
	v_exp_f32_e32 v40, v40
	v_exp_f32_e32 v41, v41
	v_pk_mul_f32 v[44:45], v[48:49], v[44:45]
	v_add_f32_e32 v40, 1.0, v40
	v_add_f32_e32 v41, 1.0, v41
	v_rcp_f32_e32 v40, v40
	v_rcp_f32_e32 v41, v41
	s_nop 0
	v_pk_mul_f32 v[14:15], v[14:15], v[40:41]
	v_cvt_pk_bf16_f32 v40, v42, v43
	v_cvt_pk_bf16_f32 v41, v44, v45
	v_cvt_pk_bf16_f32 v42, v46, v47
	v_cvt_pk_bf16_f32 v43, v14, v15
	ds_write_b128 v177, v[40:43] offset:17408
	ds_read_b128 v[40:43], v161
	ds_read_b128 v[44:47], v161 offset:16
	ds_read_b128 v[48:51], v162
	ds_read_b128 v[52:55], v162 offset:16
	s_waitcnt lgkmcnt(1)
	v_pk_fma_f32 v[14:15], v[48:49], v[24:25], v[40:41]
	v_pk_fma_f32 v[24:25], v[50:51], v[20:21], v[42:43]
	s_waitcnt lgkmcnt(0)
	v_pk_fma_f32 v[40:41], v[54:55], v[22:23], v[46:47]
	ds_read_b128 v[20:23], v162 offset:512
	v_pk_fma_f32 v[26:27], v[52:53], v[26:27], v[44:45]
	s_waitcnt lgkmcnt(0)
	v_pk_fma_f32 v[24:25], v[22:23], v[30:31], v[24:25]
	v_pk_fma_f32 v[28:29], v[20:21], v[28:29], v[14:15]
	ds_read_b128 v[20:23], v162 offset:528
	s_waitcnt lgkmcnt(0)
	v_pk_fma_f32 v[20:21], v[20:21], v[16:17], v[26:27]
	ds_read_b128 v[14:17], v162 offset:1024
	v_pk_fma_f32 v[18:19], v[22:23], v[18:19], v[40:41]
	s_waitcnt lgkmcnt(0)
	v_pk_fma_f32 v[22:23], v[14:15], v[34:35], v[28:29]
	v_pk_fma_f32 v[24:25], v[16:17], v[36:37], v[24:25]
	ds_read_b128 v[14:17], v162 offset:1040
	s_waitcnt lgkmcnt(0)
	v_pk_fma_f32 v[20:21], v[14:15], v[32:33], v[20:21]
	v_pk_fma_f32 v[16:17], v[16:17], v[12:13], v[18:19]
	ds_read_b128 v[12:15], v162 offset:1536
	v_lshlrev_b32_e32 v18, 16, v8
	v_and_b32_e32 v19, 0xffff0000, v8
	v_lshlrev_b32_e32 v8, 16, v9
	v_and_b32_e32 v9, 0xffff0000, v9
	s_waitcnt lgkmcnt(0)
	v_pk_fma_f32 v[14:15], v[14:15], v[8:9], v[24:25]
	v_pk_fma_f32 v[12:13], v[12:13], v[18:19], v[22:23]
	v_lshlrev_b32_e32 v18, 16, v10
	v_and_b32_e32 v19, 0xffff0000, v10
	v_lshlrev_b32_e32 v22, 16, v11
	v_and_b32_e32 v23, 0xffff0000, v11
	ds_read_b128 v[8:11], v162 offset:1552
	s_waitcnt lgkmcnt(0)
	v_pk_fma_f32 v[10:11], v[10:11], v[22:23], v[16:17]
	v_mul_f32_e32 v16, 0xbfb8aa3b, v12
	v_mul_f32_e32 v17, 0xbfb8aa3b, v13
	v_exp_f32_e32 v16, v16
	v_exp_f32_e32 v17, v17
	v_pk_fma_f32 v[8:9], v[8:9], v[18:19], v[20:21]
	v_add_f32_e32 v16, 1.0, v16
	v_add_f32_e32 v17, 1.0, v17
	v_rcp_f32_e32 v16, v16
	v_rcp_f32_e32 v17, v17
	s_nop 0
	v_pk_mul_f32 v[12:13], v[12:13], v[16:17]
	v_mul_f32_e32 v16, 0xbfb8aa3b, v14
	v_mul_f32_e32 v17, 0xbfb8aa3b, v15
	v_exp_f32_e32 v16, v16
	v_exp_f32_e32 v17, v17
	v_add_f32_e32 v16, 1.0, v16
	v_add_f32_e32 v17, 1.0, v17
	v_rcp_f32_e32 v16, v16
	v_rcp_f32_e32 v17, v17
	s_nop 0
	v_pk_mul_f32 v[14:15], v[14:15], v[16:17]
	v_mul_f32_e32 v16, 0xbfb8aa3b, v8
	v_mul_f32_e32 v17, 0xbfb8aa3b, v9
	v_exp_f32_e32 v16, v16
	v_exp_f32_e32 v17, v17
	v_add_f32_e32 v16, 1.0, v16
	v_add_f32_e32 v17, 1.0, v17
	v_rcp_f32_e32 v16, v16
	v_rcp_f32_e32 v17, v17
	s_nop 0
	v_pk_mul_f32 v[16:17], v[8:9], v[16:17]
	v_mul_f32_e32 v8, 0xbfb8aa3b, v10
	v_mul_f32_e32 v9, 0xbfb8aa3b, v11
	v_exp_f32_e32 v8, v8
	v_exp_f32_e32 v9, v9
	v_add_f32_e32 v8, 1.0, v8
	v_add_f32_e32 v9, 1.0, v9
	v_rcp_f32_e32 v8, v8
	v_rcp_f32_e32 v9, v9
	s_nop 0
	v_pk_mul_f32 v[18:19], v[10:11], v[8:9]
	v_cvt_pk_bf16_f32 v8, v12, v13
	v_cvt_pk_bf16_f32 v9, v14, v15
	v_cvt_pk_bf16_f32 v10, v16, v17
	v_cvt_pk_bf16_f32 v11, v18, v19
	ds_write_b128 v178, v[8:11] offset:17408
	s_cbranch_vccnz .LBB0_570
	v_mov_b32_e32 v15, v39
	s_nop 1
	v_add_f32_dpp v15, v15, v15 row_shr:1 row_mask:0xf bank_mask:0xf
	s_nop 1
	v_add_f32_dpp v15, v15, v15 row_shr:2 row_mask:0xf bank_mask:0xf
	s_nop 1
	v_add_f32_dpp v15, v15, v15 row_shr:4 row_mask:0xf bank_mask:0xf
	s_nop 1
	v_add_f32_dpp v15, v15, v15 row_shr:8 row_mask:0xf bank_mask:0xf
	s_nop 1
	v_add_f32_dpp v15, v15, v15 row_bcast:15 row_mask:0xa bank_mask:0xf
	s_nop 1
	v_add_f32_dpp v15, v15, v15 row_bcast:31 row_mask:0xc bank_mask:0xf
	v_sub_f32_e32 v10, v38, v15
	v_mov_b32_e32 v9, v10
	s_nop 1
	v_max_f32_dpp v9, v9, v9 row_shr:1 row_mask:0xf bank_mask:0xf
	s_nop 1
	v_max_f32_dpp v9, v9, v9 row_shr:2 row_mask:0xf bank_mask:0xf
	s_nop 1
	v_max_f32_dpp v9, v9, v9 row_shr:4 row_mask:0xf bank_mask:0xf
	s_nop 1
	v_max_f32_dpp v9, v9, v9 row_shr:8 row_mask:0xf bank_mask:0xf
	s_nop 1
	v_max_f32_dpp v9, v9, v9 row_bcast:15 row_mask:0xa bank_mask:0xf
	s_nop 1
	v_max_f32_dpp v9, v9, v9 row_bcast:31 row_mask:0xc bank_mask:0xf
	s_nop 1
	v_readlane_b32 s12, v15, 63
	v_readlane_b32 s13, v9, 63
	s_nop 1
	v_mov_b32_e32 v8, s12
	v_mov_b32_e32 v11, s13
	v_pk_add_f32 v[10:11], v[10:11], v[8:9] op_sel_hi:[1,0]
	s_nop 0
	v_sub_f32_e32 v9, v10, v11
	v_mul_f32_e32 v9, 0x3fb8aa3b, v9
	v_exp_f32_e32 v9, v9
	ds_write_b32 v163, v9
	s_and_saveexec_b64 s[12:13], s[48:49]
	s_cbranch_execz .LBB0_569
	s_ashr_i32 s9, s8, 31
	s_lshl_b64 s[8:9], s[8:9], 2
	s_add_u32 s14, s67, s8
	v_readlane_b32 s15, v251, 51
	s_addc_u32 s15, s15, s9
	s_add_u32 s8, s34, s8
	v_readlane_b32 s16, v251, 52
	s_addc_u32 s9, s16, s9
	s_nop 0
	global_store_dword v181, v11, s[14:15]
	global_store_dword v181, v8, s[8:9]
